# speedup vs baseline: 1.0039x; 1.0039x over previous
_Z10fwd_kernel4Args:
	s_mov_b32 s100, 0
	s_mov_b32 s101, 0
	s_load_dwordx8 s[56:63], s[0:1], 0xa0
	s_load_dwordx8 s[20:27], s[0:1], 0x80
	s_add_u32 s38, s0, 0xb8
	s_mov_b32 s70, s2
	s_addc_u32 s39, s1, 0
	s_waitcnt lgkmcnt(0)
	s_and_b32 s2, s62, 7
	s_cmp_lg_u32 s2, 0
	s_mov_b32 s43, s70
	s_cbranch_scc1 .LBB0_2
	s_ashr_i32 s3, s70, 31
	s_lshr_b32 s3, s3, 29
	s_add_i32 s3, s70, s3
	s_and_b32 s4, s3, -8
	s_ashr_i32 s2, s62, 3
	s_sub_i32 s4, s70, s4
	s_mul_i32 s2, s2, s4
	s_ashr_i32 s3, s3, 3
	s_add_i32 s43, s2, s3

.Ly_disp:
	s_cmp_eq_u32 s100, 7
	s_cbranch_scc1 .Ly_s7
	s_cmp_eq_u32 s100, 6
	s_cbranch_scc1 .Ly_s6
	s_cmp_eq_u32 s100, 5
	s_cbranch_scc1 .Ly_s5
	s_cmp_eq_u32 s100, 4
	s_cbranch_scc1 .Ly_s4
	s_cmp_eq_u32 s100, 3
	s_cbranch_scc1 .Ly_s3
	s_cmp_eq_u32 s100, 2
	s_cbranch_scc1 .Ly_s2
	v_lshl_add_u64 v[254:255], v[250:251], 0, s[22:23]
	global_store_dwordx4 v[254:255], v[246:249], off offset:256
	s_branch .Ly_dd
.Ly_s7:
	v_lshl_add_u64 v[254:255], v[250:251], 0, s[16:17]
	global_store_dwordx4 v[254:255], v[222:225], off offset:256
	s_branch .Ly_dd
.Ly_s6:
	v_lshl_add_u64 v[254:255], v[250:251], 0, s[18:19]
	global_store_dwordx4 v[254:255], v[226:229], off
	s_branch .Ly_dd
.Ly_s5:
	v_lshl_add_u64 v[254:255], v[250:251], 0, s[18:19]
	global_store_dwordx4 v[254:255], v[230:233], off offset:256
	s_branch .Ly_dd
.Ly_s4:
	v_lshl_add_u64 v[254:255], v[250:251], 0, s[20:21]
	global_store_dwordx4 v[254:255], v[234:237], off
	s_branch .Ly_dd
.Ly_s3:
	v_lshl_add_u64 v[254:255], v[250:251], 0, s[20:21]
	global_store_dwordx4 v[254:255], v[238:241], off offset:256
	s_branch .Ly_dd
.Ly_s2:
	v_lshl_add_u64 v[254:255], v[250:251], 0, s[22:23]
	global_store_dwordx4 v[254:255], v[242:245], off
.Ly_dd:
	s_sub_u32 s100, s100, 1
	s_mov_b32 s101, 1
	s_branch .Ly_ret

.LBB0_1005:
	s_cmp_lg_u32 s100, 0
	s_cbranch_scc1 .Ly_disp
.Ly_ret:
	ds_read_b128 v[140:143], v146
	ds_read_b128 v[150:153], v146 offset:1024
	ds_read_b128 v[154:157], v146 offset:2048
	ds_read_b128 v[158:161], v146 offset:3072
	ds_read_b128 v[162:165], v147
	ds_read_b128 v[166:169], v147 offset:1024
	ds_read_b128 v[170:173], v147 offset:2048
	ds_read_b128 v[174:177], v147 offset:3072
	s_add_u32 s36, s34, 0xfff80080
	s_addc_u32 s37, s35, -1
	s_cmp_eq_u32 s43, 28
	s_cselect_b32 s39, s29, s37
	s_cselect_b32 s38, s28, s36
	s_cselect_b32 s37, s31, s42
	s_cselect_b32 s36, s30, s27
	v_lshl_add_u64 v[210:211], s[34:35], 0, v[136:137]
	s_add_i32 m0, s3, 0xc000
	ds_read_b128 v[178:181], v148
	ds_read_b128 v[182:185], v148 offset:1024
	ds_read_b128 v[186:189], v148 offset:2048
	ds_read_b128 v[190:193], v148 offset:3072
	ds_read_b128 v[194:197], v148 offset:4096
	ds_read_b128 v[198:201], v148 offset:5120
	ds_read_b128 v[202:205], v148 offset:6144
	ds_read_b128 v[206:209], v148 offset:7168
	global_load_lds_dwordx4 v[210:211], off
	v_lshl_add_u64 v[210:211], s[34:35], 0, v[138:139]
	s_add_i32 m0, s3, 0xe000
	s_nop 0
	global_load_lds_dwordx4 v[210:211], off
	s_cmp_lg_u32 s101, 0
	s_cbranch_scc1 .Ly_w1r
	s_waitcnt vmcnt(8)
	s_branch .Ly_w1d

.Ly_w1d:
	s_waitcnt lgkmcnt(0)
	s_setprio 1
	s_barrier
	v_mfma_f32_16x16x32_bf16 v[124:127], v[140:143], v[178:181], v[124:127]
	v_mfma_f32_16x16x32_bf16 v[120:123], v[154:157], v[178:181], v[120:123]
	v_mfma_f32_16x16x32_bf16 v[116:119], v[140:143], v[186:189], v[116:119]
	v_mfma_f32_16x16x32_bf16 v[104:107], v[154:157], v[186:189], v[104:107]
	v_mfma_f32_16x16x32_bf16 v[92:95], v[140:143], v[194:197], v[92:95]
	v_mfma_f32_16x16x32_bf16 v[88:91], v[154:157], v[194:197], v[88:91]
	v_mfma_f32_16x16x32_bf16 v[76:79], v[140:143], v[202:205], v[76:79]
	v_mfma_f32_16x16x32_bf16 v[72:75], v[154:157], v[202:205], v[72:75]
	v_mfma_f32_16x16x32_bf16 v[124:127], v[150:153], v[182:185], v[124:127]
	v_mfma_f32_16x16x32_bf16 v[120:123], v[158:161], v[182:185], v[120:123]
	v_mfma_f32_16x16x32_bf16 v[116:119], v[150:153], v[190:193], v[116:119]
	v_mfma_f32_16x16x32_bf16 v[104:107], v[158:161], v[190:193], v[104:107]
	v_mfma_f32_16x16x32_bf16 v[92:95], v[150:153], v[198:201], v[92:95]
	v_mfma_f32_16x16x32_bf16 v[88:91], v[158:161], v[198:201], v[88:91]
	v_mfma_f32_16x16x32_bf16 v[76:79], v[150:153], v[206:209], v[76:79]
	v_mfma_f32_16x16x32_bf16 v[72:75], v[158:161], v[206:209], v[72:75]
	v_mfma_f32_16x16x32_bf16 v[112:115], v[162:165], v[178:181], v[112:115]
	v_mfma_f32_16x16x32_bf16 v[108:111], v[170:173], v[178:181], v[108:111]
	v_mfma_f32_16x16x32_bf16 v[100:103], v[162:165], v[186:189], v[100:103]
	v_mfma_f32_16x16x32_bf16 v[96:99], v[170:173], v[186:189], v[96:99]
	v_mfma_f32_16x16x32_bf16 v[84:87], v[162:165], v[194:197], v[84:87]
	v_mfma_f32_16x16x32_bf16 v[80:83], v[170:173], v[194:197], v[80:83]
	v_mfma_f32_16x16x32_bf16 v[68:71], v[162:165], v[202:205], v[68:71]
	v_mfma_f32_16x16x32_bf16 v[64:67], v[170:173], v[202:205], v[64:67]
	v_mfma_f32_16x16x32_bf16 v[112:115], v[166:169], v[182:185], v[112:115]
	v_mfma_f32_16x16x32_bf16 v[108:111], v[174:177], v[182:185], v[108:111]
	v_mfma_f32_16x16x32_bf16 v[100:103], v[166:169], v[190:193], v[100:103]
	v_mfma_f32_16x16x32_bf16 v[96:99], v[174:177], v[190:193], v[96:99]
	v_mfma_f32_16x16x32_bf16 v[84:87], v[166:169], v[198:201], v[84:87]
	v_mfma_f32_16x16x32_bf16 v[80:83], v[174:177], v[198:201], v[80:83]
	v_mfma_f32_16x16x32_bf16 v[68:71], v[166:169], v[206:209], v[68:71]
	v_mfma_f32_16x16x32_bf16 v[64:67], v[174:177], v[206:209], v[64:67]
	s_setprio 0
	s_barrier
	s_add_i32 s65, s49, s2
	v_lshl_add_u64 v[210:211], s[36:37], 0, v[130:131]
	s_mov_b32 m0, s65
	ds_read_b128 v[178:181], v148 offset:16384
	ds_read_b128 v[182:185], v148 offset:17408
	ds_read_b128 v[186:189], v148 offset:18432
	ds_read_b128 v[190:193], v148 offset:19456
	ds_read_b128 v[194:197], v148 offset:20480
	ds_read_b128 v[198:201], v148 offset:21504
	ds_read_b128 v[202:205], v148 offset:22528
	ds_read_b128 v[206:209], v148 offset:23552
	global_load_lds_dwordx4 v[210:211], off
	s_add_i32 m0, s65, 0x2000
	s_add_u32 s66, s36, 0x80000
	v_lshl_add_u64 v[212:213], s[36:37], 0, v[134:135]
	s_addc_u32 s67, s37, 0
	s_add_i32 s65, s50, s2
	global_load_lds_dwordx4 v[212:213], off
	v_lshl_add_u64 v[214:215], s[66:67], 0, v[130:131]
	s_mov_b32 m0, s65
	v_lshl_add_u64 v[216:217], s[38:39], 0, v[132:133]
	global_load_lds_dwordx4 v[214:215], off
	v_lshl_add_u64 v[214:215], s[66:67], 0, v[134:135]
	s_add_i32 m0, s65, 0x2000
	s_nop 0
	global_load_lds_dwordx4 v[214:215], off
	v_lshl_add_u64 v[214:215], s[38:39], 0, v[128:129]
	s_mov_b32 m0, s3
	s_nop 0
	global_load_lds_dwordx4 v[214:215], off
	s_mov_b32 m0, s33
	s_nop 0
	global_load_lds_dwordx4 v[216:217], off
	s_cmp_lg_u32 s101, 0
	s_cbranch_scc1 .Ly_w2r
	s_waitcnt vmcnt(8)
	s_branch .Ly_w2d
.Ly_w2r:
	s_waitcnt vmcnt(9)
	s_mov_b32 s101, 0
.Ly_w2d:
	s_waitcnt lgkmcnt(0)
	s_setprio 1
	s_barrier
	v_mfma_f32_16x16x32_bf16 v[60:63], v[140:143], v[178:181], v[60:63]
	v_mfma_f32_16x16x32_bf16 v[56:59], v[154:157], v[178:181], v[56:59]
	v_mfma_f32_16x16x32_bf16 v[44:47], v[140:143], v[186:189], v[44:47]
	v_mfma_f32_16x16x32_bf16 v[40:43], v[154:157], v[186:189], v[40:43]
	v_mfma_f32_16x16x32_bf16 v[28:31], v[140:143], v[194:197], v[28:31]
	v_mfma_f32_16x16x32_bf16 v[24:27], v[154:157], v[194:197], v[24:27]
	v_mfma_f32_16x16x32_bf16 v[12:15], v[140:143], v[202:205], v[12:15]
	v_mfma_f32_16x16x32_bf16 v[8:11], v[154:157], v[202:205], v[8:11]
	v_mfma_f32_16x16x32_bf16 v[60:63], v[150:153], v[182:185], v[60:63]
	v_mfma_f32_16x16x32_bf16 v[56:59], v[158:161], v[182:185], v[56:59]
	v_mfma_f32_16x16x32_bf16 v[44:47], v[150:153], v[190:193], v[44:47]
	v_mfma_f32_16x16x32_bf16 v[40:43], v[158:161], v[190:193], v[40:43]
	v_mfma_f32_16x16x32_bf16 v[28:31], v[150:153], v[198:201], v[28:31]
	v_mfma_f32_16x16x32_bf16 v[24:27], v[158:161], v[198:201], v[24:27]
	v_mfma_f32_16x16x32_bf16 v[12:15], v[150:153], v[206:209], v[12:15]
	v_mfma_f32_16x16x32_bf16 v[8:11], v[158:161], v[206:209], v[8:11]
	v_mfma_f32_16x16x32_bf16 v[52:55], v[162:165], v[178:181], v[52:55]
	v_mfma_f32_16x16x32_bf16 v[48:51], v[170:173], v[178:181], v[48:51]
	v_mfma_f32_16x16x32_bf16 v[36:39], v[162:165], v[186:189], v[36:39]
	v_mfma_f32_16x16x32_bf16 v[32:35], v[170:173], v[186:189], v[32:35]
	v_mfma_f32_16x16x32_bf16 v[20:23], v[162:165], v[194:197], v[20:23]
	v_mfma_f32_16x16x32_bf16 v[16:19], v[170:173], v[194:197], v[16:19]
	v_mfma_f32_16x16x32_bf16 v[4:7], v[162:165], v[202:205], v[4:7]
	v_mfma_f32_16x16x32_bf16 v[0:3], v[170:173], v[202:205], v[0:3]
	v_mfma_f32_16x16x32_bf16 v[52:55], v[166:169], v[182:185], v[52:55]
	v_mfma_f32_16x16x32_bf16 v[48:51], v[174:177], v[182:185], v[48:51]
	v_mfma_f32_16x16x32_bf16 v[36:39], v[166:169], v[190:193], v[36:39]
	v_mfma_f32_16x16x32_bf16 v[32:35], v[174:177], v[190:193], v[32:35]
	v_mfma_f32_16x16x32_bf16 v[20:23], v[166:169], v[198:201], v[20:23]
	v_mfma_f32_16x16x32_bf16 v[16:19], v[174:177], v[198:201], v[16:19]
	v_mfma_f32_16x16x32_bf16 v[4:7], v[166:169], v[206:209], v[4:7]
	v_mfma_f32_16x16x32_bf16 v[0:3], v[174:177], v[206:209], v[0:3]
	s_setprio 0
	s_barrier
	s_add_i32 s65, 0, 0x18000
	s_add_i32 s66, 0, 0x1c000
	v_add_u32_e32 v158, s65, v145
	v_add_u32_e32 v174, s66, v145
	ds_read_b128 v[140:143], v158
	ds_read_b128 v[150:153], v158 offset:1024
	ds_read_b128 v[154:157], v158 offset:2048
	ds_read_b128 v[158:161], v158 offset:3072
	ds_read_b128 v[162:165], v174
	ds_read_b128 v[166:169], v174 offset:1024
	ds_read_b128 v[170:173], v174 offset:2048
	ds_read_b128 v[174:177], v174 offset:3072
	s_add_u32 s38, s38, 0x80000
	s_addc_u32 s39, s39, 0
	s_mov_b32 m0, s40
	v_lshl_add_u64 v[220:221], s[38:39], 0, v[128:129]
	ds_read_b128 v[178:181], v148 offset:32768
	ds_read_b128 v[182:185], v148 offset:33792
	ds_read_b128 v[186:189], v148 offset:34816
	ds_read_b128 v[190:193], v148 offset:35840
	ds_read_b128 v[194:197], v148 offset:36864
	ds_read_b128 v[198:201], v148 offset:37888
	ds_read_b128 v[202:205], v148 offset:38912
	ds_read_b128 v[206:209], v148 offset:39936
	global_load_lds_dwordx4 v[220:221], off
	v_lshl_add_u64 v[220:221], s[38:39], 0, v[132:133]
	s_mov_b32 m0, s41
	s_nop 0
	global_load_lds_dwordx4 v[220:221], off
	s_waitcnt vmcnt(8)
	s_waitcnt lgkmcnt(0)
	s_setprio 1
	s_barrier
	v_mfma_f32_16x16x32_bf16 v[124:127], v[140:143], v[178:181], v[124:127]
	v_mfma_f32_16x16x32_bf16 v[120:123], v[154:157], v[178:181], v[120:123]
	v_mfma_f32_16x16x32_bf16 v[116:119], v[140:143], v[186:189], v[116:119]
	v_mfma_f32_16x16x32_bf16 v[104:107], v[154:157], v[186:189], v[104:107]
	v_mfma_f32_16x16x32_bf16 v[92:95], v[140:143], v[194:197], v[92:95]
	v_mfma_f32_16x16x32_bf16 v[88:91], v[154:157], v[194:197], v[88:91]
	v_mfma_f32_16x16x32_bf16 v[76:79], v[140:143], v[202:205], v[76:79]
	v_mfma_f32_16x16x32_bf16 v[72:75], v[154:157], v[202:205], v[72:75]
	v_mfma_f32_16x16x32_bf16 v[124:127], v[150:153], v[182:185], v[124:127]
	v_mfma_f32_16x16x32_bf16 v[120:123], v[158:161], v[182:185], v[120:123]
	v_mfma_f32_16x16x32_bf16 v[116:119], v[150:153], v[190:193], v[116:119]
	v_mfma_f32_16x16x32_bf16 v[104:107], v[158:161], v[190:193], v[104:107]
	v_mfma_f32_16x16x32_bf16 v[92:95], v[150:153], v[198:201], v[92:95]
	v_mfma_f32_16x16x32_bf16 v[88:91], v[158:161], v[198:201], v[88:91]
	v_mfma_f32_16x16x32_bf16 v[76:79], v[150:153], v[206:209], v[76:79]
	v_mfma_f32_16x16x32_bf16 v[72:75], v[158:161], v[206:209], v[72:75]
	v_mfma_f32_16x16x32_bf16 v[112:115], v[162:165], v[178:181], v[112:115]
	v_mfma_f32_16x16x32_bf16 v[108:111], v[170:173], v[178:181], v[108:111]
	v_mfma_f32_16x16x32_bf16 v[100:103], v[162:165], v[186:189], v[100:103]
	v_mfma_f32_16x16x32_bf16 v[96:99], v[170:173], v[186:189], v[96:99]
	v_mfma_f32_16x16x32_bf16 v[84:87], v[162:165], v[194:197], v[84:87]
	v_mfma_f32_16x16x32_bf16 v[80:83], v[170:173], v[194:197], v[80:83]
	v_mfma_f32_16x16x32_bf16 v[68:71], v[162:165], v[202:205], v[68:71]
	v_mfma_f32_16x16x32_bf16 v[64:67], v[170:173], v[202:205], v[64:67]
	v_mfma_f32_16x16x32_bf16 v[112:115], v[166:169], v[182:185], v[112:115]
	v_mfma_f32_16x16x32_bf16 v[108:111], v[174:177], v[182:185], v[108:111]
	v_mfma_f32_16x16x32_bf16 v[100:103], v[166:169], v[190:193], v[100:103]
	v_mfma_f32_16x16x32_bf16 v[96:99], v[174:177], v[190:193], v[96:99]
	v_mfma_f32_16x16x32_bf16 v[84:87], v[166:169], v[198:201], v[84:87]
	v_mfma_f32_16x16x32_bf16 v[80:83], v[174:177], v[198:201], v[80:83]
	v_mfma_f32_16x16x32_bf16 v[68:71], v[166:169], v[206:209], v[68:71]
	v_mfma_f32_16x16x32_bf16 v[64:67], v[174:177], v[206:209], v[64:67]
	s_setprio 0
	s_barrier
	s_add_i32 s38, s65, s2
	v_lshl_add_u64 v[210:211], v[210:211], 0, s[12:13]
	s_mov_b32 m0, s38
	ds_read_b128 v[178:181], v148 offset:49152
	ds_read_b128 v[182:185], v148 offset:50176
	ds_read_b128 v[186:189], v148 offset:51200
	ds_read_b128 v[190:193], v148 offset:52224
	ds_read_b128 v[194:197], v148 offset:53248
	ds_read_b128 v[198:201], v148 offset:54272
	ds_read_b128 v[202:205], v148 offset:55296
	ds_read_b128 v[206:209], v148 offset:56320
	global_load_lds_dwordx4 v[210:211], off
	s_add_i32 m0, s38, 0x2000
	s_add_u32 s36, s36, 0x80080
	v_lshl_add_u64 v[210:211], v[212:213], 0, s[12:13]
	s_addc_u32 s37, s37, 0
	s_add_i32 s38, s66, s2
	global_load_lds_dwordx4 v[210:211], off
	v_lshl_add_u64 v[210:211], s[36:37], 0, v[130:131]
	s_mov_b32 m0, s38
	s_nop 0
	global_load_lds_dwordx4 v[210:211], off
	v_lshl_add_u64 v[210:211], s[36:37], 0, v[134:135]
	s_add_i32 m0, s38, 0x2000
	s_nop 0
	global_load_lds_dwordx4 v[210:211], off
	v_lshl_add_u64 v[210:211], v[214:215], 0, s[12:13]
	s_mov_b32 m0, s47
	s_nop 0
	global_load_lds_dwordx4 v[210:211], off
	v_lshl_add_u64 v[210:211], v[216:217], 0, s[12:13]
	s_mov_b32 m0, s48
	s_nop 0
	global_load_lds_dwordx4 v[210:211], off
	s_waitcnt vmcnt(8)
	s_waitcnt lgkmcnt(0)
	s_setprio 1
	s_barrier
	v_mfma_f32_16x16x32_bf16 v[60:63], v[140:143], v[178:181], v[60:63]
	v_mfma_f32_16x16x32_bf16 v[56:59], v[154:157], v[178:181], v[56:59]
	v_mfma_f32_16x16x32_bf16 v[44:47], v[140:143], v[186:189], v[44:47]
	v_mfma_f32_16x16x32_bf16 v[40:43], v[154:157], v[186:189], v[40:43]
	v_mfma_f32_16x16x32_bf16 v[28:31], v[140:143], v[194:197], v[28:31]
	v_mfma_f32_16x16x32_bf16 v[24:27], v[154:157], v[194:197], v[24:27]
	v_mfma_f32_16x16x32_bf16 v[12:15], v[140:143], v[202:205], v[12:15]
	v_mfma_f32_16x16x32_bf16 v[8:11], v[154:157], v[202:205], v[8:11]
	v_mfma_f32_16x16x32_bf16 v[60:63], v[150:153], v[182:185], v[60:63]
	v_mfma_f32_16x16x32_bf16 v[56:59], v[158:161], v[182:185], v[56:59]
	v_mfma_f32_16x16x32_bf16 v[44:47], v[150:153], v[190:193], v[44:47]
	v_mfma_f32_16x16x32_bf16 v[40:43], v[158:161], v[190:193], v[40:43]
	v_mfma_f32_16x16x32_bf16 v[28:31], v[150:153], v[198:201], v[28:31]
	v_mfma_f32_16x16x32_bf16 v[24:27], v[158:161], v[198:201], v[24:27]
	v_mfma_f32_16x16x32_bf16 v[12:15], v[150:153], v[206:209], v[12:15]
	v_mfma_f32_16x16x32_bf16 v[8:11], v[158:161], v[206:209], v[8:11]
	v_mfma_f32_16x16x32_bf16 v[52:55], v[162:165], v[178:181], v[52:55]
	v_mfma_f32_16x16x32_bf16 v[48:51], v[170:173], v[178:181], v[48:51]
	v_mfma_f32_16x16x32_bf16 v[36:39], v[162:165], v[186:189], v[36:39]
	v_mfma_f32_16x16x32_bf16 v[32:35], v[170:173], v[186:189], v[32:35]
	v_mfma_f32_16x16x32_bf16 v[20:23], v[162:165], v[194:197], v[20:23]
	v_mfma_f32_16x16x32_bf16 v[16:19], v[170:173], v[194:197], v[16:19]
	v_mfma_f32_16x16x32_bf16 v[4:7], v[162:165], v[202:205], v[4:7]
	v_mfma_f32_16x16x32_bf16 v[0:3], v[170:173], v[202:205], v[0:3]
	v_mfma_f32_16x16x32_bf16 v[52:55], v[166:169], v[182:185], v[52:55]
	v_mfma_f32_16x16x32_bf16 v[48:51], v[174:177], v[182:185], v[48:51]
	v_mfma_f32_16x16x32_bf16 v[36:39], v[166:169], v[190:193], v[36:39]
	v_mfma_f32_16x16x32_bf16 v[32:35], v[174:177], v[190:193], v[32:35]
	v_mfma_f32_16x16x32_bf16 v[20:23], v[166:169], v[198:201], v[20:23]
	v_mfma_f32_16x16x32_bf16 v[16:19], v[174:177], v[198:201], v[16:19]
	v_mfma_f32_16x16x32_bf16 v[4:7], v[166:169], v[206:209], v[4:7]
	v_mfma_f32_16x16x32_bf16 v[0:3], v[174:177], v[206:209], v[0:3]
	s_setprio 0
	s_barrier
	s_add_i32 s43, s43, 2
	s_add_u32 s34, s34, 0x100
	s_addc_u32 s35, s35, 0
	s_add_u32 s27, s27, 0x100
	s_addc_u32 s42, s42, 0
	s_cmp_gt_u32 s43, 29
	s_cbranch_scc0 .LBB0_1005
	s_and_b64 vcc, exec, s[14:15]
	s_cbranch_vccz .LBB0_1008
	s_barrier
.LBB0_1008:
	s_lshl_b32 s4, s4, 8
	v_mov_b32_e32 v150, v144
	s_add_i32 s4, s4, s45
	s_nop 0
	v_and_or_b32 v142, v150, 15, s4
	v_ashrrev_i32_e32 v143, 31, v142
	v_lshl_add_u64 v[140:141], v[142:143], 2, s[6:7]
	global_load_dword v156, v[140:141], off
	global_load_dword v157, v[140:141], off offset:64
	global_load_dword v158, v[140:141], off offset:128
	global_load_dword v159, v[140:141], off offset:192
	global_load_dword v160, v[140:141], off offset:512
	global_load_dword v161, v[140:141], off offset:576
	global_load_dword v162, v[140:141], off offset:640
	global_load_dword v163, v[140:141], off offset:704
	s_lshl_b32 s4, s5, 8
	v_lshrrev_b32_e32 v140, 1, v150
	v_and_or_b32 v141, v140, 24, s4
	v_or_b32_e32 v140, 16, v142
	v_or_b32_e32 v150, s46, v141
	v_ashrrev_i32_e32 v141, 31, v140
	v_ashrrev_i32_e32 v151, 31, v150
	v_lshlrev_b64 v[152:153], 14, v[142:143]
	v_lshlrev_b64 v[154:155], 14, v[140:141]
	v_lshl_add_u64 v[150:151], v[150:151], 1, s[10:11]
	v_lshl_add_u64 v[140:141], v[150:151], 0, v[152:153]
	v_lshl_add_u64 v[152:153], v[150:151], 0, v[154:155]
	s_waitcnt vmcnt(0)
	v_fmamk_f32 v143, v156, 0x3a000000, v149
	v_fmamk_f32 v154, v157, 0x3a000000, v149
	v_mul_f32_e32 v155, 0x4b800000, v143
	v_cmp_gt_f32_e32 vcc, s51, v143
	v_mul_f32_e32 v156, 0x4b800000, v154
	v_cmp_gt_f32_e64 s[4:5], s51, v154
	v_cndmask_b32_e32 v143, v143, v155, vcc
	v_rsq_f32_e32 v155, v143
	v_cndmask_b32_e64 v154, v154, v156, s[4:5]
	v_rsq_f32_e32 v156, v154
	v_fmamk_f32 v157, v158, 0x3a000000, v149
	v_mul_f32_e32 v154, 0x45800000, v155
	v_fmamk_f32 v158, v159, 0x3a000000, v149
	v_fmamk_f32 v159, v160, 0x3a000000, v149
	v_fmamk_f32 v160, v161, 0x3a000000, v149
	v_fmamk_f32 v161, v162, 0x3a000000, v149
	v_mul_f32_e32 v162, 0x45800000, v156
	v_cndmask_b32_e32 v154, v155, v154, vcc
	v_cndmask_b32_e64 v156, v156, v162, s[4:5]
	v_pk_mul_f32 v[124:125], v[124:125], v[154:155] op_sel_hi:[1,0]
	v_pk_mul_f32 v[120:121], v[120:121], v[154:155] op_sel_hi:[1,0]
	v_pk_mul_f32 v[126:127], v[126:127], v[154:155] op_sel_hi:[1,0]
	v_pk_mul_f32 v[122:123], v[122:123], v[154:155] op_sel_hi:[1,0]
	v_pk_mul_f32 v[114:115], v[114:115], v[154:155] op_sel_hi:[1,0]
	v_pk_mul_f32 v[112:113], v[112:113], v[154:155] op_sel_hi:[1,0]
	v_pk_mul_f32 v[110:111], v[110:111], v[154:155] op_sel_hi:[1,0]
	v_pk_mul_f32 v[108:109], v[108:109], v[154:155] op_sel_hi:[1,0]
	v_pk_mul_f32 v[154:155], v[106:107], v[156:157] op_sel_hi:[1,0]
	v_max_f32_e32 v106, 0, v124
	v_max_f32_e32 v107, 0, v120
	v_max_f32_e32 v120, 0, v125
	v_max_f32_e32 v121, 0, v121
	v_max_f32_e32 v124, 0, v126
	v_max_f32_e32 v125, 0, v127
	v_mul_f32_e32 v106, v106, v106
	v_mul_f32_e32 v126, v107, v107
	v_mul_f32_e32 v107, v120, v120
	v_max_f32_e32 v122, 0, v122
	v_max_f32_e32 v123, 0, v123
	v_max_f32_e32 v112, 0, v112
	v_max_f32_e32 v108, 0, v108
	v_max_f32_e32 v113, 0, v113
	v_max_f32_e32 v109, 0, v109
	v_max_f32_e32 v114, 0, v114
	v_max_f32_e32 v115, 0, v115
	v_mul_f32_e32 v120, v121, v121
	v_mul_f32_e32 v121, v124, v124
	v_mul_f32_e32 v124, v125, v125
	v_cvt_pk_bf16_f32 v106, v106, v107
	v_cvt_pk_bf16_f32 v107, v121, v124
	v_pk_mul_f32 v[104:105], v[104:105], v[156:157] op_sel_hi:[1,0]
	v_pk_mul_f32 v[116:117], v[116:117], v[156:157] op_sel_hi:[1,0]
	v_max_f32_e32 v110, 0, v110
	v_max_f32_e32 v111, 0, v111
	v_mul_f32_e32 v122, v122, v122
	v_mul_f32_e32 v123, v123, v123
	v_mul_f32_e32 v112, v112, v112
	v_mul_f32_e32 v125, v108, v108
	v_mul_f32_e32 v113, v113, v113
	v_mul_f32_e32 v127, v109, v109
	v_mul_f32_e32 v114, v114, v114
	v_mul_f32_e32 v115, v115, v115
	v_cvt_pk_bf16_f32 v108, v126, v120
	v_cvt_pk_bf16_f32 v109, v122, v123
	global_store_dwordx4 v[140:141], v[106:109], off
	v_max_f32_e32 v104, 0, v104
	v_pk_mul_f32 v[118:119], v[118:119], v[156:157] op_sel_hi:[1,0]
	v_cvt_pk_bf16_f32 v106, v112, v113
	v_cvt_pk_bf16_f32 v107, v114, v115
	v_mul_f32_e32 v110, v110, v110
	v_mul_f32_e32 v111, v111, v111
	v_cvt_pk_bf16_f32 v108, v125, v127
	v_cvt_pk_bf16_f32 v109, v110, v111
	global_store_dwordx4 v[140:141], v[106:109], off offset:256
	v_max_f32_e32 v105, 0, v105
	v_pk_mul_f32 v[96:97], v[96:97], v[156:157] op_sel_hi:[1,0]
	v_mul_f32_e32 v107, v104, v104
	v_max_f32_e32 v104, 0, v117
	v_max_f32_e32 v106, 0, v116
	v_mul_f32_e32 v104, v104, v104
	v_mul_f32_e32 v108, v105, v105
	v_max_f32_e32 v105, 0, v118
	v_mul_f32_e32 v106, v106, v106
	v_mul_f32_e32 v105, v105, v105
	v_max_f32_e32 v109, 0, v154
	v_max_f32_e32 v110, 0, v119
	v_max_f32_e32 v111, 0, v155
	v_cvt_pk_bf16_f32 v104, v106, v104
	v_pk_mul_f32 v[102:103], v[102:103], v[156:157] op_sel_hi:[1,0]
	v_pk_mul_f32 v[100:101], v[100:101], v[156:157] op_sel_hi:[1,0]
	v_pk_mul_f32 v[98:99], v[98:99], v[156:157] op_sel_hi:[1,0]
	v_max_f32_e32 v96, 0, v96
	v_max_f32_e32 v97, 0, v97
	v_mul_f32_e32 v109, v109, v109
	v_mul_f32_e32 v110, v110, v110
	v_mul_f32_e32 v111, v111, v111
	v_cvt_pk_bf16_f32 v105, v105, v110
	v_cvt_pk_bf16_f32 v106, v107, v108
	v_cvt_pk_bf16_f32 v107, v109, v111
	global_store_dwordx4 v[152:153], v[104:107], off
	v_max_f32_e32 v98, 0, v98
	v_max_f32_e32 v100, 0, v100
	v_mul_f32_e32 v104, v96, v96
	v_max_f32_e32 v96, 0, v101
	v_mul_f32_e32 v101, v97, v97
	v_max_f32_e32 v97, 0, v102
	v_mul_f32_e32 v96, v96, v96
	v_mul_f32_e32 v97, v97, v97
	v_mul_f32_e32 v102, v98, v98
	v_max_f32_e32 v98, 0, v103
	v_max_f32_e32 v99, 0, v99
	v_mul_f32_e32 v100, v100, v100
	v_mul_f32_e32 v98, v98, v98
	v_mul_f32_e32 v99, v99, v99
	v_cvt_pk_bf16_f32 v96, v100, v96
	v_cvt_pk_bf16_f32 v97, v97, v98
	v_cvt_pk_bf16_f32 v98, v104, v101
	v_cvt_pk_bf16_f32 v99, v102, v99
	global_store_dwordx4 v[152:153], v[96:99], off offset:256
	v_cmp_gt_f32_e32 vcc, s51, v157
	v_fmamk_f32 v143, v163, 0x3a000000, v149
	v_mul_f32_e32 v97, 0x4b800000, v157
	v_cndmask_b32_e32 v97, v157, v97, vcc
	v_rsq_f32_e32 v98, v97
	v_or_b32_e32 v96, 32, v142
	v_ashrrev_i32_e32 v97, 31, v96
	v_lshlrev_b64 v[96:97], 14, v[96:97]
	v_mul_f32_e32 v99, 0x45800000, v98
	v_cndmask_b32_e32 v98, v98, v99, vcc
	v_pk_mul_f32 v[88:89], v[88:89], v[98:99] op_sel_hi:[1,0]
	v_pk_mul_f32 v[92:93], v[92:93], v[98:99] op_sel_hi:[1,0]
	v_pk_mul_f32 v[90:91], v[90:91], v[98:99] op_sel_hi:[1,0]
	v_max_f32_e32 v88, 0, v88
	v_pk_mul_f32 v[94:95], v[94:95], v[98:99] op_sel_hi:[1,0]
	v_mul_f32_e32 v99, v88, v88
	v_max_f32_e32 v88, 0, v93
	v_max_f32_e32 v89, 0, v89
	v_max_f32_e32 v90, 0, v90
	v_max_f32_e32 v92, 0, v92
	v_mul_f32_e32 v88, v88, v88
	v_mul_f32_e32 v93, v89, v89
	v_max_f32_e32 v89, 0, v94
	v_mul_f32_e32 v94, v90, v90
	v_max_f32_e32 v90, 0, v95
	v_max_f32_e32 v91, 0, v91
	v_pk_mul_f32 v[80:81], v[80:81], v[98:99] op_sel_hi:[1,0]
	v_lshl_add_u64 v[96:97], v[150:151], 0, v[96:97]
	v_mul_f32_e32 v92, v92, v92
	v_mul_f32_e32 v89, v89, v89
	v_mul_f32_e32 v90, v90, v90
	v_mul_f32_e32 v91, v91, v91
	v_cvt_pk_bf16_f32 v88, v92, v88
	v_pk_mul_f32 v[86:87], v[86:87], v[98:99] op_sel_hi:[1,0]
	v_pk_mul_f32 v[84:85], v[84:85], v[98:99] op_sel_hi:[1,0]
	v_pk_mul_f32 v[82:83], v[82:83], v[98:99] op_sel_hi:[1,0]
	v_max_f32_e32 v80, 0, v80
	v_max_f32_e32 v81, 0, v81
	v_cvt_pk_bf16_f32 v89, v89, v90
	v_cvt_pk_bf16_f32 v90, v99, v93
	v_cvt_pk_bf16_f32 v91, v94, v91
	global_store_dwordx4 v[96:97], v[88:91], off
	v_max_f32_e32 v82, 0, v82
	v_max_f32_e32 v84, 0, v84
	v_mul_f32_e32 v88, v80, v80
	v_max_f32_e32 v80, 0, v85
	v_mul_f32_e32 v85, v81, v81
	v_max_f32_e32 v81, 0, v86
	v_mul_f32_e32 v80, v80, v80
	v_mul_f32_e32 v81, v81, v81
	v_mul_f32_e32 v86, v82, v82
	v_max_f32_e32 v82, 0, v87
	v_max_f32_e32 v83, 0, v83
	v_mul_f32_e32 v84, v84, v84
	v_mul_f32_e32 v82, v82, v82
	v_mul_f32_e32 v83, v83, v83
	v_cvt_pk_bf16_f32 v80, v84, v80
	v_cvt_pk_bf16_f32 v81, v81, v82
	v_cvt_pk_bf16_f32 v82, v88, v85
	v_cvt_pk_bf16_f32 v83, v86, v83
	global_store_dwordx4 v[96:97], v[80:83], off offset:256
	v_cmp_gt_f32_e32 vcc, s51, v158
	s_mov_b64 s[4:5], -1
	v_mul_f32_e32 v81, 0x4b800000, v158
	v_cndmask_b32_e32 v81, v158, v81, vcc
	v_rsq_f32_e32 v82, v81
	v_or_b32_e32 v80, 48, v142
	v_ashrrev_i32_e32 v81, 31, v80
	v_lshlrev_b64 v[80:81], 14, v[80:81]
	v_mul_f32_e32 v83, 0x45800000, v82
	v_cndmask_b32_e32 v82, v82, v83, vcc
	v_pk_mul_f32 v[72:73], v[72:73], v[82:83] op_sel_hi:[1,0]
	v_pk_mul_f32 v[76:77], v[76:77], v[82:83] op_sel_hi:[1,0]
	v_pk_mul_f32 v[74:75], v[74:75], v[82:83] op_sel_hi:[1,0]
	v_max_f32_e32 v72, 0, v72
	v_pk_mul_f32 v[78:79], v[78:79], v[82:83] op_sel_hi:[1,0]
	v_mul_f32_e32 v83, v72, v72
	v_max_f32_e32 v72, 0, v77
	v_max_f32_e32 v73, 0, v73
	v_max_f32_e32 v74, 0, v74
	v_max_f32_e32 v76, 0, v76
	v_mul_f32_e32 v72, v72, v72
	v_mul_f32_e32 v77, v73, v73
	v_max_f32_e32 v73, 0, v78
	v_mul_f32_e32 v78, v74, v74
	v_max_f32_e32 v74, 0, v79
	v_max_f32_e32 v75, 0, v75
	v_pk_mul_f32 v[64:65], v[64:65], v[82:83] op_sel_hi:[1,0]
	v_lshl_add_u64 v[80:81], v[150:151], 0, v[80:81]
	v_mul_f32_e32 v76, v76, v76
	v_mul_f32_e32 v73, v73, v73
	v_mul_f32_e32 v74, v74, v74
	v_mul_f32_e32 v75, v75, v75
	v_cvt_pk_bf16_f32 v72, v76, v72
	v_pk_mul_f32 v[68:69], v[68:69], v[82:83] op_sel_hi:[1,0]
	v_max_f32_e32 v64, 0, v64
	v_cvt_pk_bf16_f32 v73, v73, v74
	v_cvt_pk_bf16_f32 v74, v83, v77
	v_cvt_pk_bf16_f32 v75, v78, v75
	global_store_dwordx4 v[80:81], v[72:75], off
	v_max_f32_e32 v68, 0, v68
	v_mul_f32_e32 v68, v68, v68
	v_mul_f32_e32 v72, v64, v64
	v_max_f32_e32 v64, 0, v69
	v_mul_f32_e32 v64, v64, v64
	v_cvt_pk_bf16_f32 v64, v68, v64
	v_mul_f32_e32 v68, 0x4b800000, v159
	v_cmp_gt_f32_e32 vcc, s51, v159
	v_pk_mul_f32 v[66:67], v[66:67], v[82:83] op_sel_hi:[1,0]
	v_pk_mul_f32 v[70:71], v[70:71], v[82:83] op_sel_hi:[1,0]
	v_cndmask_b32_e32 v68, v159, v68, vcc
	v_max_f32_e32 v65, 0, v65
	v_max_f32_e32 v66, 0, v66
	v_rsq_f32_e32 v68, v68
	v_mul_f32_e32 v69, v65, v65
	v_max_f32_e32 v65, 0, v70
	v_mul_f32_e32 v70, v66, v66
	v_max_f32_e32 v66, 0, v71
	v_mul_f32_e32 v65, v65, v65
	v_mul_f32_e32 v66, v66, v66
	v_max_f32_e32 v67, 0, v67
	v_mul_f32_e32 v67, v67, v67
	v_cvt_pk_bf16_f32 v65, v65, v66
	v_cvt_pk_bf16_f32 v66, v72, v69
	v_cvt_pk_bf16_f32 v67, v70, v67
	global_store_dwordx4 v[80:81], v[64:67], off offset:256
	s_nop 1
	v_mul_f32_e32 v66, 0x45800000, v68
	v_cndmask_b32_e32 v66, v68, v66, vcc
	v_pk_mul_f32 v[56:57], v[56:57], v[66:67] op_sel_hi:[1,0]
	v_pk_mul_f32 v[60:61], v[60:61], v[66:67] op_sel_hi:[1,0]
	v_pk_mul_f32 v[58:59], v[58:59], v[66:67] op_sel_hi:[1,0]
	v_max_f32_e32 v56, 0, v56
	v_pk_mul_f32 v[62:63], v[62:63], v[66:67] op_sel_hi:[1,0]
	v_max_f32_e32 v60, 0, v60
	v_mul_f32_e32 v67, v56, v56
	v_max_f32_e32 v56, 0, v61
	v_max_f32_e32 v57, 0, v57
	v_max_f32_e32 v58, 0, v58
	v_mul_f32_e32 v60, v60, v60
	v_mul_f32_e32 v56, v56, v56
	v_mul_f32_e32 v61, v57, v57
	v_max_f32_e32 v57, 0, v62
	v_mul_f32_e32 v62, v58, v58
	v_max_f32_e32 v58, 0, v63
	v_mul_f32_e32 v57, v57, v57
	v_mul_f32_e32 v58, v58, v58
	v_max_f32_e32 v59, 0, v59
	v_cvt_pk_bf16_f32 v56, v60, v56
	v_add_co_u32_e32 v60, vcc, s52, v140
	v_pk_mul_f32 v[48:49], v[48:49], v[66:67] op_sel_hi:[1,0]
	v_mul_f32_e32 v59, v59, v59
	v_cvt_pk_bf16_f32 v57, v57, v58
	v_cvt_pk_bf16_f32 v58, v67, v61
	v_addc_co_u32_e32 v61, vcc, 0, v141, vcc
	v_pk_mul_f32 v[52:53], v[52:53], v[66:67] op_sel_hi:[1,0]
	v_max_f32_e32 v48, 0, v48
	v_cvt_pk_bf16_f32 v59, v62, v59
	global_store_dwordx4 v[60:61], v[56:59], off
	v_max_f32_e32 v52, 0, v52
	v_mul_f32_e32 v52, v52, v52
	v_mul_f32_e32 v56, v48, v48
	v_max_f32_e32 v48, 0, v53
	v_mul_f32_e32 v48, v48, v48
	v_cvt_pk_bf16_f32 v48, v52, v48
	v_mul_f32_e32 v52, 0x4b800000, v160
	v_cmp_gt_f32_e32 vcc, s51, v160
	v_pk_mul_f32 v[50:51], v[50:51], v[66:67] op_sel_hi:[1,0]
	v_pk_mul_f32 v[54:55], v[54:55], v[66:67] op_sel_hi:[1,0]
	v_cndmask_b32_e32 v52, v160, v52, vcc
	v_max_f32_e32 v49, 0, v49
	v_max_f32_e32 v50, 0, v50
	v_rsq_f32_e32 v52, v52
	v_mul_f32_e32 v53, v49, v49
	v_max_f32_e32 v49, 0, v54
	v_mul_f32_e32 v54, v50, v50
	v_max_f32_e32 v50, 0, v55
	v_mul_f32_e32 v49, v49, v49
	v_mul_f32_e32 v50, v50, v50
	v_max_f32_e32 v51, 0, v51
	v_lshl_add_u64 v[64:65], v[140:141], 0, s[16:17]
	v_mul_f32_e32 v51, v51, v51
	v_cvt_pk_bf16_f32 v49, v49, v50
	v_cvt_pk_bf16_f32 v50, v56, v53
	v_cvt_pk_bf16_f32 v51, v54, v51
	s_cmp_eq_u64 s[24:25], 0
	s_cbranch_scc1 .Ly_o0
	v_mov_b32_e32 v250, v140
	v_mov_b32_e32 v251, v141
	s_mov_b32 s100, 7
	v_mov_b32_e32 v222, v48
	v_mov_b32_e32 v223, v49
	v_mov_b32_e32 v224, v50
	v_mov_b32_e32 v225, v51
	s_branch .Ly_c0
.Ly_o0:
	global_store_dwordx4 v[64:65], v[48:51], off offset:256
.Ly_c0:
	s_nop 1
	v_mul_f32_e32 v50, 0x45800000, v52
	v_cndmask_b32_e32 v50, v52, v50, vcc
	v_pk_mul_f32 v[40:41], v[40:41], v[50:51] op_sel_hi:[1,0]
	v_pk_mul_f32 v[44:45], v[44:45], v[50:51] op_sel_hi:[1,0]
	v_pk_mul_f32 v[42:43], v[42:43], v[50:51] op_sel_hi:[1,0]
	v_max_f32_e32 v40, 0, v40
	v_pk_mul_f32 v[46:47], v[46:47], v[50:51] op_sel_hi:[1,0]
	v_max_f32_e32 v44, 0, v44
	v_mul_f32_e32 v51, v40, v40
	v_max_f32_e32 v40, 0, v45
	v_max_f32_e32 v41, 0, v41
	v_max_f32_e32 v42, 0, v42
	v_mul_f32_e32 v44, v44, v44
	v_mul_f32_e32 v40, v40, v40
	v_mul_f32_e32 v45, v41, v41
	v_max_f32_e32 v41, 0, v46
	v_mul_f32_e32 v46, v42, v42
	v_max_f32_e32 v42, 0, v47
	v_mul_f32_e32 v41, v41, v41
	v_mul_f32_e32 v42, v42, v42
	v_max_f32_e32 v43, 0, v43
	v_cvt_pk_bf16_f32 v40, v44, v40
	v_add_co_u32_e32 v44, vcc, s53, v140
	v_pk_mul_f32 v[32:33], v[32:33], v[50:51] op_sel_hi:[1,0]
	v_mul_f32_e32 v43, v43, v43
	v_cvt_pk_bf16_f32 v41, v41, v42
	v_cvt_pk_bf16_f32 v42, v51, v45
	v_addc_co_u32_e32 v45, vcc, 0, v141, vcc
	v_pk_mul_f32 v[36:37], v[36:37], v[50:51] op_sel_hi:[1,0]
	v_max_f32_e32 v32, 0, v32
	v_cvt_pk_bf16_f32 v43, v46, v43
	s_cmp_eq_u64 s[24:25], 0
	s_cbranch_scc1 .Ly_o1
	v_mov_b32_e32 v226, v40
	v_mov_b32_e32 v227, v41
	v_mov_b32_e32 v228, v42
	v_mov_b32_e32 v229, v43
	s_branch .Ly_c1
.Ly_o1:
	global_store_dwordx4 v[44:45], v[40:43], off
.Ly_c1:
	v_max_f32_e32 v36, 0, v36
	v_mul_f32_e32 v36, v36, v36
	v_mul_f32_e32 v40, v32, v32
	v_max_f32_e32 v32, 0, v37
	v_mul_f32_e32 v32, v32, v32
	v_cvt_pk_bf16_f32 v32, v36, v32
	v_mul_f32_e32 v36, 0x4b800000, v161
	v_cmp_gt_f32_e32 vcc, s51, v161
	v_pk_mul_f32 v[34:35], v[34:35], v[50:51] op_sel_hi:[1,0]
	v_pk_mul_f32 v[38:39], v[38:39], v[50:51] op_sel_hi:[1,0]
	v_cndmask_b32_e32 v36, v161, v36, vcc
	v_max_f32_e32 v33, 0, v33
	v_max_f32_e32 v34, 0, v34
	v_rsq_f32_e32 v36, v36
	v_mul_f32_e32 v37, v33, v33
	v_max_f32_e32 v33, 0, v38
	v_mul_f32_e32 v38, v34, v34
	v_max_f32_e32 v34, 0, v39
	v_mul_f32_e32 v33, v33, v33
	v_mul_f32_e32 v34, v34, v34
	v_max_f32_e32 v35, 0, v35
	v_lshl_add_u64 v[48:49], v[140:141], 0, s[18:19]
	v_mul_f32_e32 v35, v35, v35
	v_cvt_pk_bf16_f32 v33, v33, v34
	v_cvt_pk_bf16_f32 v34, v40, v37
	v_cvt_pk_bf16_f32 v35, v38, v35
	s_cmp_eq_u64 s[24:25], 0
	s_cbranch_scc1 .Ly_o2
	v_mov_b32_e32 v230, v32
	v_mov_b32_e32 v231, v33
	v_mov_b32_e32 v232, v34
	v_mov_b32_e32 v233, v35
	s_branch .Ly_c2
.Ly_o2:
	global_store_dwordx4 v[48:49], v[32:35], off offset:256
.Ly_c2:
	s_nop 1
	v_mul_f32_e32 v34, 0x45800000, v36
	v_cndmask_b32_e32 v34, v36, v34, vcc
	v_pk_mul_f32 v[24:25], v[24:25], v[34:35] op_sel_hi:[1,0]
	v_pk_mul_f32 v[28:29], v[28:29], v[34:35] op_sel_hi:[1,0]
	v_pk_mul_f32 v[26:27], v[26:27], v[34:35] op_sel_hi:[1,0]
	v_max_f32_e32 v24, 0, v24
	v_pk_mul_f32 v[30:31], v[30:31], v[34:35] op_sel_hi:[1,0]
	v_max_f32_e32 v28, 0, v28
	v_mul_f32_e32 v35, v24, v24
	v_max_f32_e32 v24, 0, v29
	v_max_f32_e32 v25, 0, v25
	v_max_f32_e32 v26, 0, v26
	v_mul_f32_e32 v28, v28, v28
	v_mul_f32_e32 v24, v24, v24
	v_mul_f32_e32 v29, v25, v25
	v_max_f32_e32 v25, 0, v30
	v_mul_f32_e32 v30, v26, v26
	v_max_f32_e32 v26, 0, v31
	v_mul_f32_e32 v25, v25, v25
	v_mul_f32_e32 v26, v26, v26
	v_max_f32_e32 v27, 0, v27
	v_cvt_pk_bf16_f32 v24, v28, v24
	v_add_co_u32_e32 v28, vcc, s54, v140
	v_pk_mul_f32 v[16:17], v[16:17], v[34:35] op_sel_hi:[1,0]
	v_mul_f32_e32 v27, v27, v27
	v_cvt_pk_bf16_f32 v25, v25, v26
	v_cvt_pk_bf16_f32 v26, v35, v29
	v_addc_co_u32_e32 v29, vcc, 0, v141, vcc
	v_pk_mul_f32 v[20:21], v[20:21], v[34:35] op_sel_hi:[1,0]
	v_max_f32_e32 v16, 0, v16
	v_cvt_pk_bf16_f32 v27, v30, v27
	s_cmp_eq_u64 s[24:25], 0
	s_cbranch_scc1 .Ly_o3
	v_mov_b32_e32 v234, v24
	v_mov_b32_e32 v235, v25
	v_mov_b32_e32 v236, v26
	v_mov_b32_e32 v237, v27
	s_branch .Ly_c3
.Ly_o3:
	global_store_dwordx4 v[28:29], v[24:27], off
.Ly_c3:
	v_max_f32_e32 v20, 0, v20
	v_mul_f32_e32 v20, v20, v20
	v_mul_f32_e32 v24, v16, v16
	v_max_f32_e32 v16, 0, v21
	v_mul_f32_e32 v16, v16, v16
	v_cvt_pk_bf16_f32 v16, v20, v16
	v_mul_f32_e32 v20, 0x4b800000, v143
	v_cmp_gt_f32_e32 vcc, s51, v143
	v_pk_mul_f32 v[18:19], v[18:19], v[34:35] op_sel_hi:[1,0]
	v_pk_mul_f32 v[22:23], v[22:23], v[34:35] op_sel_hi:[1,0]
	v_cndmask_b32_e32 v20, v143, v20, vcc
	v_max_f32_e32 v17, 0, v17
	v_max_f32_e32 v18, 0, v18
	v_rsq_f32_e32 v20, v20
	v_mul_f32_e32 v21, v17, v17
	v_max_f32_e32 v17, 0, v22
	v_mul_f32_e32 v22, v18, v18
	v_max_f32_e32 v18, 0, v23
	v_mul_f32_e32 v17, v17, v17
	v_mul_f32_e32 v18, v18, v18
	v_max_f32_e32 v19, 0, v19
	v_lshl_add_u64 v[32:33], v[140:141], 0, s[20:21]
	v_mul_f32_e32 v19, v19, v19
	v_cvt_pk_bf16_f32 v17, v17, v18
	v_cvt_pk_bf16_f32 v18, v24, v21
	v_cvt_pk_bf16_f32 v19, v22, v19
	s_cmp_eq_u64 s[24:25], 0
	s_cbranch_scc1 .Ly_o4
	v_mov_b32_e32 v238, v16
	v_mov_b32_e32 v239, v17
	v_mov_b32_e32 v240, v18
	v_mov_b32_e32 v241, v19
	s_branch .Ly_c4
.Ly_o4:
	global_store_dwordx4 v[32:33], v[16:19], off offset:256
.Ly_c4:
	s_nop 1
	v_mul_f32_e32 v18, 0x45800000, v20
	v_cndmask_b32_e32 v18, v20, v18, vcc
	v_pk_mul_f32 v[8:9], v[8:9], v[18:19] op_sel_hi:[1,0]
	v_pk_mul_f32 v[12:13], v[12:13], v[18:19] op_sel_hi:[1,0]
	v_pk_mul_f32 v[10:11], v[10:11], v[18:19] op_sel_hi:[1,0]
	v_max_f32_e32 v8, 0, v8
	v_pk_mul_f32 v[14:15], v[14:15], v[18:19] op_sel_hi:[1,0]
	v_max_f32_e32 v12, 0, v12
	v_mul_f32_e32 v19, v8, v8
	v_max_f32_e32 v8, 0, v13
	v_max_f32_e32 v9, 0, v9
	v_max_f32_e32 v10, 0, v10
	v_mul_f32_e32 v12, v12, v12
	v_mul_f32_e32 v8, v8, v8
	v_mul_f32_e32 v13, v9, v9
	v_max_f32_e32 v9, 0, v14
	v_mul_f32_e32 v14, v10, v10
	v_max_f32_e32 v10, 0, v15
	v_mul_f32_e32 v9, v9, v9
	v_mul_f32_e32 v10, v10, v10
	v_max_f32_e32 v11, 0, v11
	v_cvt_pk_bf16_f32 v8, v12, v8
	v_add_co_u32_e32 v12, vcc, s55, v140
	v_pk_mul_f32 v[2:3], v[2:3], v[18:19] op_sel_hi:[1,0]
	v_pk_mul_f32 v[0:1], v[0:1], v[18:19] op_sel_hi:[1,0]
	v_mul_f32_e32 v11, v11, v11
	v_cvt_pk_bf16_f32 v9, v9, v10
	v_cvt_pk_bf16_f32 v10, v19, v13
	v_addc_co_u32_e32 v13, vcc, 0, v141, vcc
	v_pk_mul_f32 v[6:7], v[6:7], v[18:19] op_sel_hi:[1,0]
	v_pk_mul_f32 v[4:5], v[4:5], v[18:19] op_sel_hi:[1,0]
	v_max_f32_e32 v0, 0, v0
	v_max_f32_e32 v1, 0, v1
	v_max_f32_e32 v2, 0, v2
	v_cvt_pk_bf16_f32 v11, v14, v11
	s_cmp_eq_u64 s[24:25], 0
	s_cbranch_scc1 .Ly_o5
	v_mov_b32_e32 v242, v8
	v_mov_b32_e32 v243, v9
	v_mov_b32_e32 v244, v10
	v_mov_b32_e32 v245, v11
	s_branch .Ly_c5
.Ly_o5:
	global_store_dwordx4 v[12:13], v[8:11], off
.Ly_c5:
	v_max_f32_e32 v3, 0, v3
	v_lshl_add_u64 v[16:17], v[140:141], 0, s[22:23]
	v_mul_f32_e32 v8, v0, v0
	v_max_f32_e32 v0, 0, v5
	v_mul_f32_e32 v5, v1, v1
	v_max_f32_e32 v1, 0, v6
	v_mul_f32_e32 v6, v2, v2
	v_max_f32_e32 v2, 0, v7
	v_max_f32_e32 v4, 0, v4
	v_mul_f32_e32 v0, v0, v0
	v_mul_f32_e32 v1, v1, v1
	v_mul_f32_e32 v2, v2, v2
	v_mul_f32_e32 v3, v3, v3
	s_andn2_b64 vcc, exec, s[24:25]
	v_mul_f32_e32 v4, v4, v4
	v_cvt_pk_bf16_f32 v0, v4, v0
	v_cvt_pk_bf16_f32 v1, v1, v2
	v_cvt_pk_bf16_f32 v2, v8, v5
	v_cvt_pk_bf16_f32 v3, v6, v3
	s_cmp_eq_u64 s[24:25], 0
	s_cbranch_scc1 .Ly_o6
	v_mov_b32_e32 v246, v0
	v_mov_b32_e32 v247, v1
	v_mov_b32_e32 v248, v2
	v_mov_b32_e32 v249, v3
	s_branch .Ly_c6
.Ly_o6:
	global_store_dwordx4 v[16:17], v[0:3], off offset:256
.Ly_c6:
	s_cbranch_vccnz .LBB0_997
	s_andn2_b64 vcc, exec, s[0:1]
	s_cbranch_vccnz .LBB0_996
	s_barrier
	s_branch .LBB0_996

	.amdhsa_kernel _Z10fwd_kernel4Args
		.amdhsa_group_segment_fixed_size 0
		.amdhsa_private_segment_fixed_size 0
		.amdhsa_kernarg_size 440
		.amdhsa_user_sgpr_count 2
		.amdhsa_user_sgpr_dispatch_ptr 0
		.amdhsa_user_sgpr_queue_ptr 0
		.amdhsa_user_sgpr_kernarg_segment_ptr 1
		.amdhsa_user_sgpr_dispatch_id 0
		.amdhsa_user_sgpr_kernarg_preload_length 0
		.amdhsa_user_sgpr_kernarg_preload_offset 0
		.amdhsa_user_sgpr_private_segment_size 0
		.amdhsa_uses_dynamic_stack 0
		.amdhsa_enable_private_segment 0
		.amdhsa_system_sgpr_workgroup_id_x 1
		.amdhsa_system_sgpr_workgroup_id_y 0
		.amdhsa_system_sgpr_workgroup_id_z 0
		.amdhsa_system_sgpr_workgroup_info 0
		.amdhsa_system_vgpr_workitem_id 2
		.amdhsa_next_free_vgpr 256
		.amdhsa_next_free_sgpr 102
		.amdhsa_accum_offset 256
		.amdhsa_reserve_vcc 1
		.amdhsa_float_round_mode_32 0
		.amdhsa_float_round_mode_16_64 0
		.amdhsa_float_denorm_mode_32 3
		.amdhsa_float_denorm_mode_16_64 3
		.amdhsa_dx10_clamp 1
		.amdhsa_ieee_mode 1
		.amdhsa_fp16_overflow 0
		.amdhsa_tg_split 0
		.amdhsa_exception_fp_ieee_invalid_op 0
		.amdhsa_exception_fp_denorm_src 0
		.amdhsa_exception_fp_ieee_div_zero 0
		.amdhsa_exception_fp_ieee_overflow 0
		.amdhsa_exception_fp_ieee_underflow 0
		.amdhsa_exception_fp_ieee_inexact 0
		.amdhsa_exception_int_div_zero 0
	.end_amdhsa_kernel

amdhsa.kernels:
  - .agpr_count:     0
    .args:
      - .offset:         0
        .size:           184
        .value_kind:     by_value
      - .offset:         184
        .size:           4
        .value_kind:     hidden_block_count_x
      - .offset:         188
        .size:           4
        .value_kind:     hidden_block_count_y
      - .offset:         192
        .size:           4
        .value_kind:     hidden_block_count_z
      - .offset:         196
        .size:           2
        .value_kind:     hidden_group_size_x
      - .offset:         198
        .size:           2
        .value_kind:     hidden_group_size_y
      - .offset:         200
        .size:           2
        .value_kind:     hidden_group_size_z
      - .offset:         202
        .size:           2
        .value_kind:     hidden_remainder_x
      - .offset:         204
        .size:           2
        .value_kind:     hidden_remainder_y
      - .offset:         206
        .size:           2
        .value_kind:     hidden_remainder_z
      - .offset:         224
        .size:           8
        .value_kind:     hidden_global_offset_x
      - .offset:         232
        .size:           8
        .value_kind:     hidden_global_offset_y
      - .offset:         240
        .size:           8
        .value_kind:     hidden_global_offset_z
      - .offset:         248
        .size:           2
        .value_kind:     hidden_grid_dims
      - .offset:         272
        .size:           8
        .value_kind:     hidden_multigrid_sync_arg
      - .offset:         304
        .size:           4
        .value_kind:     hidden_dynamic_lds_size
    .group_segment_fixed_size: 0
    .kernarg_segment_align: 8
    .kernarg_segment_size: 440
    .language:       OpenCL C
    .language_version:
      - 2
      - 0
    .max_flat_workgroup_size: 512
    .name:           _Z10fwd_kernel4Args
    .private_segment_fixed_size: 0
    .sgpr_count:     108
    .sgpr_spill_count: 55
    .symbol:         _Z10fwd_kernel4Args.kd
    .uniform_work_group_size: 1
    .uses_dynamic_stack: false
    .vgpr_count:     256
    .vgpr_spill_count: 0
    .wavefront_size: 64
